# attention unit prologue: drop early vmcnt(0) Q drain so Q loads overlap first K/V LDS-DMA
# speedup vs baseline: 1.0087x; 1.0087x over previous
; template <int MODE> ...
;     asm volatile("" : "+v"(tid)); lane = tid & 63;
;     const int r32 = lane & 31, hi = lane >> 5;
;     const int w = __builtin_amdgcn_readfirstlane(tid >> 6);
;     bf16x8 qf[4];
; #pragma unroll
;     for (int d0 = 0; d0 < 4; ++d0) qf[d0] = *(const bf16x8*)(Qrow + r32 * 64 + d0 * 16 + hi * 8);
;     const int kkey = 8 * w + (lane >> 3), kch = (lane & 7) ^ ((kkey >> 1) & 7);
;     const int vkey = 8 * w + ((lane >> 2) & 7), vch = 4 * ((lane >> 5) & 1) + (lane & 3);
;     const bf16_t* kg = Kb + kkey * 64 + kch * 8;
;     const bf16_t* vg = Vb + vkey * 64 + vch * 8;
;     const unsigned ring0 = (unsigned)(unsigned long)ring;
;     const unsigned kdst = (unsigned)__builtin_amdgcn_readfirstlane(ring0 + w * 1024), vdst = kdst + 8192;
;     const float cq = (MODE == 1) ? tab[qpos0 + r32] : 0.f;
;     const float cfar = (MODE == 0) ? tab[256] : 0.f;
;     const unsigned vl = v_lane_off(lane);
;     St S; st_init(S);
;     asm volatile("" :: "v"(qf[0]), "v"(qf[1]), "v"(qf[2]), "v"(qf[3]));
;     constexpr bool REV = (MODE == 1);
; __device__ __forceinline__ void phase2(const Params& P, LAS unsigned char* lds, int tid, int lane, int wave) {
;     ...
;             const int mode = it < 8, u = it & 7;
;             const int hc = 8 * u + wave;
;             const size_t qrow = (size_t)b * SEQ + hc * 32;
;             const size_t ho = (size_t)(b * 8 + h) * 2048 * 64;
;             const bf16_t* Qrow = (const bf16_t*)(P.ws + WS_SEG + (size_t)(mode ? 4 : 0) * SEG_STRIDE) + ho + (size_t)hc * 32 * 64;
;             const bf16_t* Grow = (const bf16_t*)(P.ws + WS_SEG + (size_t)(mode ? 7 : 3) * SEG_STRIDE) + ho + (size_t)hc * 32 * 64;
;             const bf16_t* Kb = (const bf16_t*)(P.ws + WS_SEG + (size_t)(mode ? 5 : 1) * SEG_STRIDE) + ho;
;             const bf16_t* Vb = (const bf16_t*)(P.ws + WS_SEG + (size_t)(mode ? 6 : 2) * SEG_STRIDE) + ho;
;             bf16_t* Yrow = (bf16_t*)(P.ws + WS_H) + qrow * 1024 + (mode ? 512 : 0) + h * 64;
;             if (mode) {
;                 att::super_unit<1>(Qrow, Kb, Vb, 0, 4 * u + 4, 0, (hc >> 1) + 1, hc * 32, c2p, Yrow, Grow, work, tid, lane);
;             } else {
;                 const int n = hc >> 1, lo = (n - 8) < 0 ? 0 : (n - 8), t0 = (4 * u - 8) < 0 ? 0 : (4 * u - 8);
;                 att::super_unit<0>(Qrow, Kb, Vb, t0, 4 * u + 4, lo, n + 1, hc * 32, rb2, Yrow, Grow, work, tid, lane);
.LBB0_598:
	s_and_b32 s2, s99, 7
	s_lshl_b32 s0, s2, 3
	s_add_i32 s0, s86, s0
	s_and_b32 s4, s21, 7
	s_lshr_b32 s6, s0, 1
	s_lshl_b32 s0, s4, 3
	s_add_i32 s40, s0, s86
	s_lshl_b32 s12, s40, 5
	s_cmp_lt_u32 s21, 8
	s_mov_b32 s1, 0x14a00000
	s_cselect_b32 s0, 0x10800000, 0
	s_cselect_b32 s5, s1, 0x4200000
	s_mov_b32 s1, 0x18c00000
	s_mov_b32 s41, s13
	s_cselect_b32 s3, 0x1ce00000, s33
	s_cselect_b32 s7, s1, 0x8400000
	s_cselect_b32 s10, 0x400, 0
	s_add_u32 s8, s29, s0
	s_addc_u32 s9, s98, 0
	s_lshl_b64 s[0:1], s[40:41], 12
	s_add_u32 s42, s8, s0
	s_addc_u32 s43, s9, s1
	s_add_u32 s3, s29, s3
	s_addc_u32 s9, s98, 0
	s_add_u32 s8, s3, s0
	s_addc_u32 s9, s9, s1
	s_add_u32 s36, s29, s5
	s_addc_u32 s37, s98, 0
	s_add_u32 s38, s29, s7
	s_addc_u32 s39, s98, 0
	s_lshl_b64 s[0:1], s[12:13], 11
	s_add_u32 s0, s11, s0
	s_addc_u32 s1, s19, s1
	s_add_u32 s0, s0, s10
	s_addc_u32 s1, s1, 0
	v_readlane_b32 s16, v240, 45
	v_readlane_b32 s17, v240, 46
	s_add_u32 s16, s0, s16
	s_addc_u32 s17, s1, s17
	s_cmp_gt_u32 s21, 7
	s_mov_b64 s[0:1], -1
	s_cbranch_scc0 .LBB0_634
	v_mov_b32_e32 v143, v120
	v_mov_b32_e32 v5, v1
	v_and_b32_e32 v144, 31, v143
	v_bfe_u32 v6, v143, 5, 1
	v_lshlrev_b32_e32 v0, 7, v144
	v_lshl_add_u64 v[2:3], s[42:43], 0, v[0:1]
	v_lshlrev_b32_e32 v4, 4, v6
	v_lshl_add_u64 v[2:3], v[2:3], 0, v[4:5]
	global_load_dwordx4 v[80:83], v[2:3], off
	global_load_dwordx4 v[84:87], v[2:3], off offset:32
	global_load_dwordx4 v[88:91], v[2:3], off offset:64
	global_load_dwordx4 v[92:95], v[2:3], off offset:96
	s_lshl_b32 s3, s4, 2
	s_add_i32 s0, s3, -8
	s_cmp_gt_u32 s4, 1
	v_readfirstlane_b32 s4, v143
	v_and_b32_e32 v2, 32, v143
	v_lshlrev_b32_e32 v4, 3, v143
	s_cselect_b32 s44, s0, 0
	s_ashr_i32 s7, s4, 6
	v_bfe_u32 v142, v143, 3, 3
	v_and_or_b32 v2, v4, 24, v2
	s_lshl_b32 s4, s7, 3
	v_lshlrev_b32_e32 v4, 1, v2
	v_or_b32_e32 v2, s4, v142
	v_lshrrev_b32_e32 v7, 2, v143
	v_lshrrev_b32_e32 v11, 1, v2
	v_and_or_b32 v9, v7, 7, s4
	v_lshlrev_b32_e32 v8, 6, v2
	v_xor_b32_e32 v2, v11, v143
	v_lshlrev_b32_e32 v10, 6, v9
	v_ashrrev_i32_e32 v9, 31, v8
	v_lshlrev_b32_e32 v2, 4, v2
	v_mov_b32_e32 v3, v1
	s_lshl_b32 s5, s7, 10
	v_ashrrev_i32_e32 v11, 31, v10
	v_lshl_add_u64 v[8:9], v[8:9], 1, s[36:37]
	v_and_b32_e32 v2, 0x70, v2
	s_mov_b32 s1, s13
	ds_read_b32 v145, v1 offset:17664
	s_lshl_b32 s0, s44, 13
	s_add_i32 s4, s5, 0
	v_lshl_add_u64 v[10:11], v[10:11], 1, s[38:39]
	v_lshl_add_u64 v[2:3], v[8:9], 0, v[2:3]
	s_add_i32 s24, s4, 0x4800
	v_lshl_add_u64 v[4:5], v[10:11], 0, v[4:5]
	v_lshl_add_u64 v[8:9], v[2:3], 0, s[0:1]
	s_add_i32 s25, s4, 0x6800
	s_add_i32 s15, s3, 4
	s_mov_b32 s5, m0
	s_mov_b32 m0, s24
	s_nop 0
	global_load_lds_dwordx4 v[8:9], off
	s_mov_b32 m0, s5
	v_lshl_add_u64 v[8:9], v[4:5], 0, s[0:1]
	s_mov_b32 s0, m0
	s_mov_b32 m0, s25
	s_nop 0
	global_load_lds_dwordx4 v[8:9], off
	s_mov_b32 m0, s0
	s_or_b32 s5, s44, 1
	s_cmp_ge_u32 s5, s15
	s_mov_b64 s[0:1], -1
	s_cbranch_scc0 .LBB0_601
	s_waitcnt vmcnt(0) lgkmcnt(0)
	s_barrier
	s_cbranch_execnz .LBB0_603
	s_branch .LBB0_602

; __device__ __forceinline__ int crow(int r, int hi) { return (r & 3) + 8 * (r >> 2) + 4 * hi; }
; __device__ __forceinline__ unsigned v_lane_off(int lane) { return (unsigned)((4 * (lane >> 5) + ((lane & 15) >> 2)) * 64 + ((lane >> 4) & 1) * 32 + (lane & 3) * 8); }
; template <int MODE>
; __device__ __forceinline__ void step64(St& S, const bf16x8 (&qf)[4], int t, int qpos0, bool diag, bool first, float cq, float cfar, const LAS float* tab,
;                                        const LAS unsigned char* buf, unsigned vaddr, int r32, int hi) {
;     ...
;     if (MODE == 1 && diag) {
;         const int qrel = qpos0 - t * 64 + r32;
; #pragma unroll
;         for (int r = 0; r < 16; ++r) { if (crow(r, hi) > qrel) sa[r] = -1e30f; if (crow(r, hi) + 32 > qrel) sb[r] = -1e30f; }
; template <int MODE> ...
;     asm volatile("" : "+v"(tid)); lane = tid & 63;
;     const int r32 = lane & 31, hi = lane >> 5;
;     const int w = __builtin_amdgcn_readfirstlane(tid >> 6);
;     bf16x8 qf[4];
; #pragma unroll
;     for (int d0 = 0; d0 < 4; ++d0) qf[d0] = *(const bf16x8*)(Qrow + r32 * 64 + d0 * 16 + hi * 8);
;     const int kkey = 8 * w + (lane >> 3), kch = (lane & 7) ^ ((kkey >> 1) & 7);
;     const int vkey = 8 * w + ((lane >> 2) & 7), vch = 4 * ((lane >> 5) & 1) + (lane & 3);
;     const bf16_t* kg = Kb + kkey * 64 + kch * 8;
;     const bf16_t* vg = Vb + vkey * 64 + vch * 8;
;     const unsigned ring0 = (unsigned)(unsigned long)ring;
;     const unsigned kdst = (unsigned)__builtin_amdgcn_readfirstlane(ring0 + w * 1024), vdst = kdst + 8192;
;     const float cq = (MODE == 1) ? tab[qpos0 + r32] : 0.f;
;     const float cfar = (MODE == 0) ? tab[256] : 0.f;
;     const unsigned vl = v_lane_off(lane);
;     St S; st_init(S);
;     asm volatile("" :: "v"(qf[0]), "v"(qf[1]), "v"(qf[2]), "v"(qf[3]));
;     constexpr bool REV = (MODE == 1);
;     ...
;     int s0 = 0, s1 = 16384, s2 = 32768;
;     glds16(kg + (size_t)SU_T(T0) * 4096, kdst + s0); glds16(vg + (size_t)SU_T(T0) * 4096, vdst + s0);
;     if (T0 + 1 < T1) { glds16(kg + (size_t)SU_T(T0 + 1) * 4096, kdst + s1); glds16(vg + (size_t)SU_T(T0 + 1) * 4096, vdst + s1);
;                        asm volatile("s_waitcnt vmcnt(2) lgkmcnt(0)\n\ts_barrier" ::: "memory"); }
;     else             { asm volatile("s_waitcnt vmcnt(0) lgkmcnt(0)\n\ts_barrier" ::: "memory"); }
.LBB0_634:
	s_and_b64 vcc, exec, s[0:1]
	s_cbranch_vccz .LBB0_597
	v_mov_b32_e32 v123, v120
	v_mov_b32_e32 v5, v1
	v_and_b32_e32 v124, 31, v123
	v_bfe_u32 v6, v123, 5, 1
	v_lshlrev_b32_e32 v0, 7, v124
	v_lshl_add_u64 v[2:3], s[42:43], 0, v[0:1]
	v_lshlrev_b32_e32 v4, 4, v6
	v_lshl_add_u64 v[2:3], v[2:3], 0, v[4:5]
	global_load_dwordx4 v[80:83], v[2:3], off
	global_load_dwordx4 v[84:87], v[2:3], off offset:32
	global_load_dwordx4 v[88:91], v[2:3], off offset:64
	global_load_dwordx4 v[92:95], v[2:3], off offset:96
	s_lshl_b32 s4, s21, 14
	s_lshl_b32 s1, s12, 2
	s_mov_b32 s3, s13
	s_or_b32 s2, s4, 0x3000
	v_readfirstlane_b32 s10, v123
	s_sub_i32 s15, 0, s6
	s_add_i32 s1, s1, 0
	v_lshrrev_b32_e32 v8, 3, v123
	v_bfe_u32 v9, v123, 2, 2
	v_lshlrev_b32_e32 v10, 1, v123
	s_lshl_b64 s[6:7], s[2:3], 1
	v_lshrrev_b32_e32 v125, 1, v123
	s_ashr_i32 s2, s10, 6
	v_bfe_u32 v122, v123, 3, 3
	v_lshlrev_b32_e32 v5, 3, v123
	v_lshl_add_u32 v12, v124, 2, s1
	v_and_or_b32 v8, v8, 4, v9
	v_and_b32_e32 v9, 32, v10
	v_bitop3_b32 v10, v6, v125, 7 bitop3:0x78
	s_lshl_b32 s1, s2, 3
	v_lshrrev_b32_e32 v2, 2, v123
	v_bfe_u32 v11, v123, 1, 3
	v_and_b32_e32 v5, 24, v5
	v_lshlrev_b32_e32 v8, 6, v8
	v_lshl_or_b32 v143, v10, 4, v0
	v_or_b32_e32 v10, s1, v122
	v_bitop3_b32 v13, v6, v11, 2 bitop3:0x36
	v_bitop3_b32 v14, v6, v11, 4 bitop3:0x36
	v_bitop3_b32 v11, v6, v11, 6 bitop3:0x36
	v_lshlrev_b32_e32 v16, 2, v6
	v_and_or_b32 v6, v123, 32, v5
	v_and_or_b32 v2, v2, 7, s1
	v_or3_b32 v147, v5, v9, v8
	v_lshrrev_b32_e32 v5, 1, v10
	v_lshlrev_b32_e32 v8, 6, v10
	v_lshlrev_b32_e32 v10, 6, v2
	v_xor_b32_e32 v2, v5, v123
	v_lshl_or_b32 v146, v11, 4, v0
	v_ashrrev_i32_e32 v9, 31, v8
	v_ashrrev_i32_e32 v11, 31, v10
	v_lshlrev_b32_e32 v2, 4, v2
	v_mov_b32_e32 v3, v1
	v_mov_b32_e32 v7, v1
	s_mov_b32 s5, s13
	s_bitset1_b32 s4, 13
	s_lshl_b32 s3, s2, 10
	v_lshlrev_b32_e32 v6, 1, v6
	v_lshl_add_u64 v[8:9], v[8:9], 1, s[36:37]
	v_lshl_add_u64 v[10:11], v[10:11], 1, s[38:39]
	v_and_b32_e32 v2, 0x70, v2
	s_lshl_b64 s[4:5], s[4:5], 1
	s_add_i32 s1, s3, 0
	v_lshl_add_u64 v[6:7], v[10:11], 0, v[6:7]
	v_lshl_add_u64 v[2:3], v[8:9], 0, v[2:3]
	ds_read_b32 v142, v12
	v_lshl_or_b32 v144, v13, 4, v0
	v_lshl_or_b32 v145, v14, 4, v0
	s_add_i32 s20, s1, 0x4800
	v_lshl_add_u64 v[10:11], v[6:7], 0, s[4:5]
	v_lshl_add_u64 v[12:13], v[2:3], 0, s[6:7]
	v_lshl_add_u64 v[14:15], v[2:3], 0, s[4:5]
	s_add_i32 s3, s1, 0x6800
	v_lshl_add_u64 v[8:9], v[6:7], 0, s[6:7]
	s_lshr_b32 s28, s40, 1
	s_add_i32 s10, s1, 0x8800
	s_add_i32 s1, s1, 0xa800
	v_or_b32_e32 v0, 32, v16
	v_or_b32_e32 v17, 33, v16
	v_or_b32_e32 v5, 2, v16
	v_or_b32_e32 v18, 42, v16
	v_or_b32_e32 v19, 11, v16
	v_or_b32_e32 v20, 43, v16
	v_or_b32_e32 v21, 16, v16
	v_or_b32_e32 v22, 48, v16
	v_or_b32_e32 v23, 17, v16
	s_mov_b32 s4, m0
	s_mov_b32 m0, s20
	s_nop 0
	global_load_lds_dwordx4 v[12:13], off
	s_mov_b32 m0, s4
	v_or_b32_e32 v12, 40, v16
	s_mov_b32 s4, m0
	s_mov_b32 m0, s3
	s_nop 0
	global_load_lds_dwordx4 v[8:9], off
	s_mov_b32 m0, s4
	v_or_b32_e32 v8, 34, v16
	s_mov_b32 s4, m0
	s_mov_b32 m0, s10
	s_nop 0
	global_load_lds_dwordx4 v[14:15], off
	s_mov_b32 m0, s4
	v_or_b32_e32 v14, 41, v16
	s_mov_b32 s4, m0
	s_mov_b32 m0, s1
	s_nop 0
	global_load_lds_dwordx4 v[10:11], off
	s_mov_b32 m0, s4
	s_lshl_b32 s1, s28, 6
	s_sub_i32 s1, s12, s1
	v_or_b32_e32 v15, 10, v16
	v_or_b32_e32 v37, s1, v124
	s_waitcnt vmcnt(2) lgkmcnt(0)
	s_barrier
	v_or_b32_e32 v9, 3, v16
	v_or_b32_e32 v10, 35, v16
	v_or_b32_e32 v11, 8, v16
	v_or_b32_e32 v13, 9, v16
	v_or_b32_e32 v24, 49, v16
	v_or_b32_e32 v25, 18, v16
	v_or_b32_e32 v26, 50, v16
	v_or_b32_e32 v27, 19, v16
	v_or_b32_e32 v28, 51, v16
	v_or_b32_e32 v29, 24, v16
	v_or_b32_e32 v30, 56, v16
	v_or_b32_e32 v31, 25, v16
	v_or_b32_e32 v32, 57, v16
	v_or_b32_e32 v33, 26, v16
	v_or_b32_e32 v34, 58, v16
	v_or_b32_e32 v35, 27, v16
	v_or_b32_e32 v36, 59, v16
	v_cmp_gt_i32_e64 s[56:57], v14, v37
	v_cmp_gt_i32_e64 s[58:59], v15, v37
	v_mov_b32_e32 v14, v1
	v_mov_b32_e32 v15, v1
	s_mov_b32 s23, s86
	s_lshl_b32 s33, s21, 2
	v_cmp_gt_i32_e64 s[34:35], v16, v37
	v_cmp_gt_i32_e64 s[36:37], v0, v37
	v_cmp_lt_i32_e64 s[38:39], v16, v37
	v_cmp_gt_i32_e64 s[40:41], v17, v37
	v_cmp_gt_i32_e64 s[42:43], v5, v37
	v_cmp_gt_i32_e64 s[44:45], v8, v37
	v_cmp_gt_i32_e64 s[46:47], v9, v37
	v_cmp_gt_i32_e64 s[48:49], v10, v37
	v_cmp_gt_i32_e64 s[50:51], v11, v37
	v_cmp_gt_i32_e64 s[52:53], v12, v37
	v_cmp_gt_i32_e64 s[54:55], v13, v37
	v_cmp_gt_i32_e64 s[60:61], v18, v37
	v_cmp_gt_i32_e64 s[62:63], v19, v37
	v_cmp_gt_i32_e64 s[64:65], v20, v37
	v_cmp_gt_i32_e64 s[66:67], v21, v37
	v_cmp_gt_i32_e64 s[68:69], v22, v37
	v_cmp_gt_i32_e64 s[70:71], v23, v37
	v_cmp_gt_i32_e64 s[72:73], v24, v37
	v_cmp_gt_i32_e64 s[74:75], v25, v37
	v_cmp_gt_i32_e64 s[76:77], v26, v37
	v_cmp_gt_i32_e64 s[78:79], v27, v37
	v_cmp_gt_i32_e64 s[80:81], v28, v37
	v_cmp_gt_i32_e64 s[82:83], v29, v37
	v_cmp_gt_i32_e64 s[84:85], v30, v37
	v_cmp_gt_i32_e64 s[86:87], v31, v37
	v_cmp_gt_i32_e64 s[88:89], v32, v37
	v_cmp_gt_i32_e64 s[90:91], v33, v37
	v_cmp_gt_i32_e64 s[92:93], v34, v37
	v_cmp_gt_i32_e64 s[94:95], v35, v37
	v_cmp_gt_i32_e64 s[96:97], v36, v37
	v_lshl_add_u64 v[116:117], v[6:7], 0, s[30:31]
	v_lshl_add_u64 v[118:119], v[2:3], 0, s[30:31]
	v_add_u32_e32 v148, s14, v4
	v_mov_b32_e32 v0, v1
	v_mov_b32_e32 v2, v1
	v_mov_b32_e32 v3, v1
	v_mov_b32_e32 v4, v1
	v_mov_b32_e32 v5, v1
	v_mov_b32_e32 v6, v1
	v_mov_b32_e32 v7, v1
	v_mov_b32_e32 v8, v1
	v_mov_b32_e32 v9, v1
	v_mov_b32_e32 v10, v1
	v_mov_b32_e32 v11, v1
	v_mov_b32_e32 v12, v1
	v_mov_b32_e32 v13, v1
	v_mov_b64_e32 v[30:31], v[14:15]
	v_mov_b64_e32 v[46:47], v[14:15]
	s_mov_b32 s0, 0
	s_mov_b32 s19, 2
	s_add_i32 s33, s33, 4
	v_mov_b32_e32 v150, 0
	s_mov_b32 s12, 0x8000
	s_movk_i32 s10, 0x4000
	s_mov_b32 s1, s18
	v_mov_b32_e32 v149, 0
	v_mov_b64_e32 v[28:29], v[12:13]
	v_mov_b64_e32 v[26:27], v[10:11]
	v_mov_b64_e32 v[24:25], v[8:9]
	v_mov_b64_e32 v[22:23], v[6:7]
	v_mov_b64_e32 v[20:21], v[4:5]
	v_mov_b64_e32 v[18:19], v[2:3]
	v_mov_b64_e32 v[16:17], v[0:1]
	v_mov_b64_e32 v[44:45], v[12:13]
	v_mov_b64_e32 v[42:43], v[10:11]
	v_mov_b64_e32 v[40:41], v[8:9]
	v_mov_b64_e32 v[38:39], v[6:7]
	v_mov_b64_e32 v[36:37], v[4:5]
	v_mov_b64_e32 v[34:35], v[2:3]
	v_mov_b64_e32 v[32:33], v[0:1]
